# transpose phase: task->(channel group, position) remap so 4 adjacent lanes store 64 contiguous bytes of one row (16 rows x 64B per store instead of 64 rows x 16B)
# speedup vs baseline: 1.0028x; 1.0028x over previous
; #define LAS __attribute__((address_space(3)))
; __device__ __forceinline__ void transpose_phase(LAS unsigned char* lds, const Args& a, int bid, int G, int tid) {
;     ...
;         for (int task = tid; task < np * 32; task += 512) { const int pos = task % np, cc = task / np;
;             const LAS unsigned short* t = (const LAS unsigned short*)(tile + ((8 * cc) * 72 + pos) * 2);
;             u32x4 o; o.x = (unsigned)t[0] | ((unsigned)t[72] << 16); o.y = (unsigned)t[144] | ((unsigned)t[216] << 16);
;             o.z = (unsigned)t[288] | ((unsigned)t[360] << 16); o.w = (unsigned)t[432] | ((unsigned)t[504] << 16);
;             *(u32x4*)(OUT + (size_t)seq_row(s, p0 + pos) * DM + c0 + 8 * cc) = o; }
.LBB0_1763:
	s_ff1_i32_b32 s24, s19
	s_add_i32 s25, s19, -1
	v_lshrrev_b32_e32 v57, 2, v42
	v_and_b32_e32 v58, s25, v57
	v_lshrrev_b32_e32 v57, s24, v57
	v_and_b32_e32 v59, 3, v42
	v_lshl_or_b32 v57, v57, 2, v59
	v_lshl_or_b32 v57, v57, s24, v58
	v_sub_u32_e32 v45, 0, v57
	v_max_i32_e32 v45, v57, v45
	v_mul_hi_u32 v46, v45, v41
	v_mul_lo_u32 v48, v46, s19
	v_sub_u32_e32 v45, v45, v48
	v_add_u32_e32 v49, 1, v46
	v_cmp_le_u32_e32 vcc, s19, v45
	v_subrev_u32_e32 v48, s19, v45
	v_ashrrev_i32_e32 v43, 31, v57
	v_cndmask_b32_e32 v46, v46, v49, vcc
	v_cndmask_b32_e32 v45, v45, v48, vcc
	v_add_u32_e32 v48, 1, v46
	v_cmp_le_u32_e32 vcc, s19, v45
	s_movk_i32 s24, 0x240
	v_mul_i32_i24_e32 v51, 0x240, v43
	v_cndmask_b32_e32 v45, v46, v48, vcc
	v_xor_b32_e32 v45, v45, v43
	v_sub_u32_e32 v43, v45, v43
	v_add_u32_e32 v44, s11, v57
	v_mul_lo_u32 v45, v45, s24
	v_mul_lo_u32 v52, v43, s19
	v_lshlrev_b32_e32 v46, 3, v43
	v_mad_u64_u32 v[48:49], s[24:25], s15, v43, v[44:45]
	v_sub_u32_e32 v43, v45, v52
	v_sub_u32_e32 v43, v43, v51
	v_mov_b32_e32 v47, s22
	v_mov_b32_e32 v50, s21
	v_cmp_gt_i32_e32 vcc, 16, v48
	v_add_u32_e32 v43, v57, v43
	v_lshl_add_u32 v43, v43, 1, s20
	v_cndmask_b32_e32 v45, v47, v50, vcc
	v_sub_u32_e32 v45, v45, v52
	ds_read_u16 v50, v43
	ds_read_u16 v51, v43 offset:144
	ds_read_u16 v52, v43 offset:288
	ds_read_u16 v53, v43 offset:432
	ds_read_u16 v54, v43 offset:576
	ds_read_u16 v55, v43 offset:720
	ds_read_u16 v56, v43 offset:864
	ds_read_u16 v43, v43 offset:1008
	v_add_u32_e32 v44, v44, v45
	v_ashrrev_i32_e32 v45, 31, v44
	v_add_u32_e32 v42, 0x200, v42
	v_lshlrev_b64 v[44:45], 11, v[44:45]
	v_ashrrev_i32_e32 v47, 31, v46
	v_cmp_le_i32_e32 vcc, s10, v42
	v_lshl_add_u64 v[44:45], s[2:3], 0, v[44:45]
	s_or_b64 s[8:9], vcc, s[8:9]
	v_lshl_add_u64 v[48:49], v[46:47], 1, v[44:45]
	s_waitcnt lgkmcnt(6)
	v_lshl_or_b32 v44, v51, 16, v50
	s_waitcnt lgkmcnt(4)
	v_lshl_or_b32 v45, v53, 16, v52
	s_waitcnt lgkmcnt(2)
	v_lshl_or_b32 v46, v55, 16, v54
	s_waitcnt lgkmcnt(0)
	v_lshl_or_b32 v47, v43, 16, v56
	global_store_dwordx4 v[48:49], v[44:47], off
	s_andn2_b64 exec, exec, s[8:9]
	s_cbranch_execnz .LBB0_1763
	s_branch .LBB0_1714
